# loop bookkeeping (pointer/counter updates) moved from behind the last MFMA burst into the load segment of the P1 and merged-GEMM K-loops
# speedup vs baseline: 1.0136x; 1.0037x over previous
.LBB0_181:
	ds_read_b128 v[144:147], v157
	ds_read_b128 v[148:151], v157 offset:1024
	ds_read_b128 v[162:165], v157 offset:2048
	ds_read_b128 v[166:169], v157 offset:3072
	s_add_u32 s30, s28, 0xfff80080
	s_addc_u32 s31, s29, -1
	s_cmp_eq_u32 s54, 28
	s_cselect_b32 s35, s2, s31
	s_cselect_b32 s34, s3, s30
	s_cselect_b32 s31, s7, s27
	s_cselect_b32 s30, s9, s11
	v_lshl_add_u64 v[152:153], s[28:29], 0, v[136:137]
	s_add_i32 m0, s39, 0xc000
	ds_read_b128 v[170:173], v158
	ds_read_b128 v[174:177], v158 offset:1024
	ds_read_b128 v[178:181], v158 offset:2048
	ds_read_b128 v[186:189], v158 offset:3072
	ds_read_b128 v[194:197], v158 offset:4096
	ds_read_b128 v[198:201], v158 offset:5120
	ds_read_b128 v[202:205], v158 offset:6144
	ds_read_b128 v[206:209], v158 offset:7168
	global_load_lds_dwordx4 v[152:153], off
	v_lshl_add_u64 v[152:153], s[28:29], 0, v[138:139]
	s_add_i32 m0, s39, 0xe000
	s_nop 0
	global_load_lds_dwordx4 v[152:153], off
	ds_read_b128 v[210:213], v159
	ds_read_b128 v[214:217], v159 offset:1024
	ds_read_b128 v[218:221], v159 offset:2048
	ds_read_b128 v[222:225], v159 offset:3072
	s_waitcnt lgkmcnt(0)
	s_barrier
	s_setprio 1
	v_mfma_f32_16x16x32_bf16 v[124:127], v[144:147], v[170:173], v[124:127]
	v_mfma_f32_16x16x32_bf16 v[120:123], v[162:165], v[170:173], v[120:123]
	v_mfma_f32_16x16x32_bf16 v[108:111], v[144:147], v[178:181], v[108:111]
	v_mfma_f32_16x16x32_bf16 v[104:107], v[162:165], v[178:181], v[104:107]
	v_mfma_f32_16x16x32_bf16 v[92:95], v[144:147], v[194:197], v[92:95]
	v_mfma_f32_16x16x32_bf16 v[88:91], v[162:165], v[194:197], v[88:91]
	v_mfma_f32_16x16x32_bf16 v[76:79], v[144:147], v[202:205], v[76:79]
	v_mfma_f32_16x16x32_bf16 v[72:75], v[162:165], v[202:205], v[72:75]
	v_mfma_f32_16x16x32_bf16 v[124:127], v[148:151], v[174:177], v[124:127]
	v_mfma_f32_16x16x32_bf16 v[120:123], v[166:169], v[174:177], v[120:123]
	v_mfma_f32_16x16x32_bf16 v[108:111], v[148:151], v[186:189], v[108:111]
	v_mfma_f32_16x16x32_bf16 v[104:107], v[166:169], v[186:189], v[104:107]
	v_mfma_f32_16x16x32_bf16 v[92:95], v[148:151], v[198:201], v[92:95]
	v_mfma_f32_16x16x32_bf16 v[88:91], v[166:169], v[198:201], v[88:91]
	v_mfma_f32_16x16x32_bf16 v[76:79], v[148:151], v[206:209], v[76:79]
	v_mfma_f32_16x16x32_bf16 v[72:75], v[166:169], v[206:209], v[72:75]
	v_mfma_f32_16x16x32_bf16 v[116:119], v[210:213], v[170:173], v[116:119]
	v_mfma_f32_16x16x32_bf16 v[112:115], v[218:221], v[170:173], v[112:115]
	v_mfma_f32_16x16x32_bf16 v[100:103], v[210:213], v[178:181], v[100:103]
	v_mfma_f32_16x16x32_bf16 v[96:99], v[218:221], v[178:181], v[96:99]
	v_mfma_f32_16x16x32_bf16 v[84:87], v[210:213], v[194:197], v[84:87]
	v_mfma_f32_16x16x32_bf16 v[80:83], v[218:221], v[194:197], v[80:83]
	v_mfma_f32_16x16x32_bf16 v[68:71], v[210:213], v[202:205], v[68:71]
	v_mfma_f32_16x16x32_bf16 v[64:67], v[218:221], v[202:205], v[64:67]
	v_mfma_f32_16x16x32_bf16 v[116:119], v[214:217], v[174:177], v[116:119]
	v_mfma_f32_16x16x32_bf16 v[112:115], v[222:225], v[174:177], v[112:115]
	v_mfma_f32_16x16x32_bf16 v[100:103], v[214:217], v[186:189], v[100:103]
	v_mfma_f32_16x16x32_bf16 v[96:99], v[222:225], v[186:189], v[96:99]
	v_mfma_f32_16x16x32_bf16 v[84:87], v[214:217], v[198:201], v[84:87]
	v_mfma_f32_16x16x32_bf16 v[80:83], v[222:225], v[198:201], v[80:83]
	v_mfma_f32_16x16x32_bf16 v[68:71], v[214:217], v[206:209], v[68:71]
	v_mfma_f32_16x16x32_bf16 v[64:67], v[222:225], v[206:209], v[64:67]
	s_setprio 0
	s_barrier
	s_add_i32 s55, s48, s38
	v_lshl_add_u64 v[152:153], s[30:31], 0, v[130:131]
	s_mov_b32 m0, s55
	s_nop 0
	global_load_lds_dwordx4 v[152:153], off
	v_lshl_add_u64 v[182:183], s[30:31], 0, v[134:135]
	s_add_i32 m0, s55, 0x2000
	s_nop 0
	global_load_lds_dwordx4 v[182:183], off
	s_mov_b32 m0, s39
	v_lshl_add_u64 v[190:191], s[34:35], 0, v[128:129]
	ds_read_b128 v[170:173], v158 offset:16384
	ds_read_b128 v[174:177], v158 offset:17408
	ds_read_b128 v[178:181], v158 offset:18432
	ds_read_b128 v[186:189], v158 offset:19456
	ds_read_b128 v[194:197], v158 offset:20480
	ds_read_b128 v[198:201], v158 offset:21504
	ds_read_b128 v[202:205], v158 offset:22528
	ds_read_b128 v[206:209], v158 offset:23552
	global_load_lds_dwordx4 v[190:191], off
	v_lshl_add_u64 v[226:227], s[34:35], 0, v[132:133]
	s_mov_b32 m0, s40
	s_nop 0
	global_load_lds_dwordx4 v[226:227], off
	s_add_u32 s56, s30, 0x80000
	s_addc_u32 s57, s31, 0
	s_add_i32 s55, s49, s38
	v_lshl_add_u64 v[246:247], s[56:57], 0, v[130:131]
	s_mov_b32 m0, s55
	s_nop 0
	global_load_lds_dwordx4 v[246:247], off
	v_lshl_add_u64 v[248:249], s[56:57], 0, v[134:135]
	s_add_i32 m0, s55, 0x2000
	s_nop 0
	global_load_lds_dwordx4 v[248:249], off
	s_add_i32 s55, 0, 0x18000
	v_add_u32_e32 v161, s55, v155
	s_waitcnt vmcnt(6)
	s_waitcnt lgkmcnt(0)
	s_barrier
	s_setprio 1
	v_mfma_f32_16x16x32_bf16 v[60:63], v[144:147], v[170:173], v[60:63]
	v_mfma_f32_16x16x32_bf16 v[56:59], v[162:165], v[170:173], v[56:59]
	v_mfma_f32_16x16x32_bf16 v[44:47], v[144:147], v[178:181], v[44:47]
	v_mfma_f32_16x16x32_bf16 v[40:43], v[162:165], v[178:181], v[40:43]
	v_mfma_f32_16x16x32_bf16 v[28:31], v[144:147], v[194:197], v[28:31]
	v_mfma_f32_16x16x32_bf16 v[24:27], v[162:165], v[194:197], v[24:27]
	v_mfma_f32_16x16x32_bf16 v[12:15], v[144:147], v[202:205], v[12:15]
	v_mfma_f32_16x16x32_bf16 v[8:11], v[162:165], v[202:205], v[8:11]
	v_mfma_f32_16x16x32_bf16 v[60:63], v[148:151], v[174:177], v[60:63]
	v_mfma_f32_16x16x32_bf16 v[56:59], v[166:169], v[174:177], v[56:59]
	v_mfma_f32_16x16x32_bf16 v[44:47], v[148:151], v[186:189], v[44:47]
	v_mfma_f32_16x16x32_bf16 v[40:43], v[166:169], v[186:189], v[40:43]
	v_mfma_f32_16x16x32_bf16 v[28:31], v[148:151], v[198:201], v[28:31]
	v_mfma_f32_16x16x32_bf16 v[24:27], v[166:169], v[198:201], v[24:27]
	v_mfma_f32_16x16x32_bf16 v[12:15], v[148:151], v[206:209], v[12:15]
	v_mfma_f32_16x16x32_bf16 v[8:11], v[166:169], v[206:209], v[8:11]
	v_mfma_f32_16x16x32_bf16 v[52:55], v[210:213], v[170:173], v[52:55]
	v_mfma_f32_16x16x32_bf16 v[48:51], v[218:221], v[170:173], v[48:51]
	v_mfma_f32_16x16x32_bf16 v[36:39], v[210:213], v[178:181], v[36:39]
	v_mfma_f32_16x16x32_bf16 v[32:35], v[218:221], v[178:181], v[32:35]
	v_mfma_f32_16x16x32_bf16 v[20:23], v[210:213], v[194:197], v[20:23]
	v_mfma_f32_16x16x32_bf16 v[16:19], v[218:221], v[194:197], v[16:19]
	v_mfma_f32_16x16x32_bf16 v[4:7], v[210:213], v[202:205], v[4:7]
	v_mfma_f32_16x16x32_bf16 v[0:3], v[218:221], v[202:205], v[0:3]
	v_mfma_f32_16x16x32_bf16 v[52:55], v[214:217], v[174:177], v[52:55]
	v_mfma_f32_16x16x32_bf16 v[48:51], v[222:225], v[174:177], v[48:51]
	v_mfma_f32_16x16x32_bf16 v[36:39], v[214:217], v[186:189], v[36:39]
	v_mfma_f32_16x16x32_bf16 v[32:35], v[222:225], v[186:189], v[32:35]
	v_mfma_f32_16x16x32_bf16 v[20:23], v[214:217], v[198:201], v[20:23]
	v_mfma_f32_16x16x32_bf16 v[16:19], v[222:225], v[198:201], v[16:19]
	v_mfma_f32_16x16x32_bf16 v[4:7], v[214:217], v[206:209], v[4:7]
	v_mfma_f32_16x16x32_bf16 v[0:3], v[222:225], v[206:209], v[0:3]
	s_setprio 0
	s_barrier
	ds_read_b128 v[144:147], v161
	ds_read_b128 v[148:151], v161 offset:1024
	ds_read_b128 v[162:165], v161 offset:2048
	ds_read_b128 v[166:169], v161 offset:3072
	s_add_u32 s34, s34, 0x80000
	s_addc_u32 s35, s35, 0
	s_mov_b32 m0, s41
	v_lshl_add_u64 v[250:251], s[34:35], 0, v[128:129]
	ds_read_b128 v[170:173], v158 offset:32768
	ds_read_b128 v[174:177], v158 offset:33792
	ds_read_b128 v[178:181], v158 offset:34816
	ds_read_b128 v[186:189], v158 offset:35840
	ds_read_b128 v[194:197], v158 offset:36864
	ds_read_b128 v[198:201], v158 offset:37888
	ds_read_b128 v[202:205], v158 offset:38912
	ds_read_b128 v[206:209], v158 offset:39936
	global_load_lds_dwordx4 v[250:251], off
	v_lshl_add_u64 v[252:253], s[34:35], 0, v[132:133]
	s_mov_b32 m0, s42
	s_nop 0
	global_load_lds_dwordx4 v[252:253], off
	v_add_u32_e32 v161, 0x1c000, v155
	ds_read_b128 v[210:213], v161
	ds_read_b128 v[214:217], v161 offset:1024
	ds_read_b128 v[218:221], v161 offset:2048
	ds_read_b128 v[222:225], v161 offset:3072
	s_waitcnt lgkmcnt(0)
	s_barrier
	s_setprio 1
	v_mfma_f32_16x16x32_bf16 v[124:127], v[144:147], v[170:173], v[124:127]
	v_mfma_f32_16x16x32_bf16 v[120:123], v[162:165], v[170:173], v[120:123]
	v_mfma_f32_16x16x32_bf16 v[108:111], v[144:147], v[178:181], v[108:111]
	v_mfma_f32_16x16x32_bf16 v[104:107], v[162:165], v[178:181], v[104:107]
	v_mfma_f32_16x16x32_bf16 v[92:95], v[144:147], v[194:197], v[92:95]
	v_mfma_f32_16x16x32_bf16 v[88:91], v[162:165], v[194:197], v[88:91]
	v_mfma_f32_16x16x32_bf16 v[76:79], v[144:147], v[202:205], v[76:79]
	v_mfma_f32_16x16x32_bf16 v[72:75], v[162:165], v[202:205], v[72:75]
	v_mfma_f32_16x16x32_bf16 v[124:127], v[148:151], v[174:177], v[124:127]
	v_mfma_f32_16x16x32_bf16 v[120:123], v[166:169], v[174:177], v[120:123]
	v_mfma_f32_16x16x32_bf16 v[108:111], v[148:151], v[186:189], v[108:111]
	v_mfma_f32_16x16x32_bf16 v[104:107], v[166:169], v[186:189], v[104:107]
	v_mfma_f32_16x16x32_bf16 v[92:95], v[148:151], v[198:201], v[92:95]
	v_mfma_f32_16x16x32_bf16 v[88:91], v[166:169], v[198:201], v[88:91]
	v_mfma_f32_16x16x32_bf16 v[76:79], v[148:151], v[206:209], v[76:79]
	v_mfma_f32_16x16x32_bf16 v[72:75], v[166:169], v[206:209], v[72:75]
	v_mfma_f32_16x16x32_bf16 v[116:119], v[210:213], v[170:173], v[116:119]
	v_mfma_f32_16x16x32_bf16 v[112:115], v[218:221], v[170:173], v[112:115]
	v_mfma_f32_16x16x32_bf16 v[100:103], v[210:213], v[178:181], v[100:103]
	v_mfma_f32_16x16x32_bf16 v[96:99], v[218:221], v[178:181], v[96:99]
	v_mfma_f32_16x16x32_bf16 v[84:87], v[210:213], v[194:197], v[84:87]
	v_mfma_f32_16x16x32_bf16 v[80:83], v[218:221], v[194:197], v[80:83]
	v_mfma_f32_16x16x32_bf16 v[68:71], v[210:213], v[202:205], v[68:71]
	v_mfma_f32_16x16x32_bf16 v[64:67], v[218:221], v[202:205], v[64:67]
	v_mfma_f32_16x16x32_bf16 v[116:119], v[214:217], v[174:177], v[116:119]
	v_mfma_f32_16x16x32_bf16 v[112:115], v[222:225], v[174:177], v[112:115]
	v_mfma_f32_16x16x32_bf16 v[100:103], v[214:217], v[186:189], v[100:103]
	v_mfma_f32_16x16x32_bf16 v[96:99], v[222:225], v[186:189], v[96:99]
	v_mfma_f32_16x16x32_bf16 v[84:87], v[214:217], v[198:201], v[84:87]
	v_mfma_f32_16x16x32_bf16 v[80:83], v[222:225], v[198:201], v[80:83]
	v_mfma_f32_16x16x32_bf16 v[68:71], v[214:217], v[206:209], v[68:71]
	v_mfma_f32_16x16x32_bf16 v[64:67], v[222:225], v[206:209], v[64:67]
	s_setprio 0
	s_barrier
; __device__ __forceinline__ unsigned pk2(float lo, float hi) { unsigned r; asm("v_cvt_pk_bf16_f32 %0, %1, %2" : "=v"(r) : "v"(lo), "v"(hi)); return r; }
; template <class Epi>
; __device__ __forceinline__ void gemm_phase(LAS unsigned char* lds, const GemmD g, const Epi& E) {
;     ...
;         for (int t = 0; t < nt; t += 2) PG8_KITER(t);
;     __device__ __forceinline__ void operator()(const f32x4 (&acc)[2][2][4][2], const Unit& u, int wr, int wc, int fr, int fq) const {
;         const int row0 = u.pm * BM + wr * 64 + fr, col0 = u.pn * BM + wc * 32 + 8 * fq;
;         const bool sig = (u.pn >= 36 && u.pn < 52), isdt = (u.pn == 52);
; #pragma unroll
;         for (int ai = 0; ai < 2; ++ai)
; #pragma unroll
;             for (int m = 0; m < 4; ++m) { const int row = row0 + ai * HALF + m * 16;
; #pragma unroll
;                 for (int bj = 0; bj < 2; ++bj) { const f32x4 v0 = acc[ai][bj][m][0], v1 = acc[ai][bj][m][1]; const int col = col0 + bj * HALF;
;                     if (sig) {
;                         const int c = (col - C_GS) >> 1;
;                         float ra[4], gp[4];
; #pragma unroll
;                         for (int j = 0; j < 4; ++j) { const float ea = __expf(-fminf(fmaxf(v0[j], -30.f), 30.f)), eb = __expf(-fminf(fmaxf(v1[j], -30.f), 30.f)); gp[j] = __builtin_amdgcn_rcpf(1.0f + eb); ra[j] = (1.0f + eb) * __builtin_amdgcn_rcpf(1.0f + ea); }
;                         u32x2 wr_, wg; wr_.x = pk2(ra[0], ra[1]); wr_.y = pk2(ra[2], ra[3]); wg.x = pk2(gp[0], gp[1]); wg.y = pk2(gp[2], gp[3]);
;                         *(u32x2*)(proj + (size_t)row * NPROJ + C_GS + c) = wr_;
;                         *(u32x2*)(proj + (size_t)row * NPROJ + C_GP + c) = wg;
;                     } else {
;                         u32x4 w; w.x = pk2(v0[0], v0[1]); w.y = pk2(v0[2], v0[3]); w.z = pk2(v1[0], v1[1]); w.w = pk2(v1[2], v1[3]);
;                         *(u32x4*)(proj + (size_t)row * NPROJ + col) = w;
;                         if (isdt && col < C_DT + 32) { float* d = dtraw + (size_t)row * 32 + (col - C_DT); *(f32x4*)d = v0; *(f32x4*)(d + 4) = v1; } } } }
	s_add_i32 s34, 0, 0x1c000
	s_add_i32 s35, s55, s38
	v_lshl_add_u64 v[152:153], v[152:153], 0, s[0:1]
	s_mov_b32 m0, s35
	s_nop 0
	global_load_lds_dwordx4 v[152:153], off
	v_lshl_add_u64 v[152:153], v[182:183], 0, s[0:1]
	s_add_i32 m0, s35, 0x2000
	s_nop 0
	global_load_lds_dwordx4 v[152:153], off
	s_mov_b32 m0, s44
	v_lshl_add_u64 v[152:153], v[190:191], 0, s[0:1]
	ds_read_b128 v[170:173], v158 offset:49152
	ds_read_b128 v[174:177], v158 offset:50176
	ds_read_b128 v[178:181], v158 offset:51200
	ds_read_b128 v[186:189], v158 offset:52224
	ds_read_b128 v[194:197], v158 offset:53248
	ds_read_b128 v[198:201], v158 offset:54272
	ds_read_b128 v[202:205], v158 offset:55296
	ds_read_b128 v[206:209], v158 offset:56320
	global_load_lds_dwordx4 v[152:153], off
	v_lshl_add_u64 v[152:153], v[226:227], 0, s[0:1]
	s_mov_b32 m0, s45
	s_nop 0
	global_load_lds_dwordx4 v[152:153], off
	s_add_u32 s30, s30, 0x80080
	s_addc_u32 s31, s31, 0
	s_add_i32 s34, s34, s38
	v_lshl_add_u64 v[246:247], s[30:31], 0, v[130:131]
	s_mov_b32 m0, s34
	s_nop 0
	global_load_lds_dwordx4 v[246:247], off
	v_lshl_add_u64 v[248:249], s[30:31], 0, v[134:135]
	s_add_i32 m0, s34, 0x2000
	s_nop 0
	global_load_lds_dwordx4 v[248:249], off
	s_add_i32 s54, s54, 2
	s_add_u32 s28, s28, 0x100
	s_addc_u32 s29, s29, 0
	s_add_u32 s11, s11, 0x100
	s_addc_u32 s27, s27, 0
	s_cmp_gt_u32 s54, 29
	s_waitcnt vmcnt(6)
	s_waitcnt lgkmcnt(0)
	s_barrier
	s_setprio 1
	v_mfma_f32_16x16x32_bf16 v[60:63], v[144:147], v[170:173], v[60:63]
	v_mfma_f32_16x16x32_bf16 v[56:59], v[162:165], v[170:173], v[56:59]
	v_mfma_f32_16x16x32_bf16 v[44:47], v[144:147], v[178:181], v[44:47]
	v_mfma_f32_16x16x32_bf16 v[40:43], v[162:165], v[178:181], v[40:43]
	v_mfma_f32_16x16x32_bf16 v[28:31], v[144:147], v[194:197], v[28:31]
	v_mfma_f32_16x16x32_bf16 v[24:27], v[162:165], v[194:197], v[24:27]
	v_mfma_f32_16x16x32_bf16 v[12:15], v[144:147], v[202:205], v[12:15]
	v_mfma_f32_16x16x32_bf16 v[8:11], v[162:165], v[202:205], v[8:11]
	v_mfma_f32_16x16x32_bf16 v[60:63], v[148:151], v[174:177], v[60:63]
	v_mfma_f32_16x16x32_bf16 v[56:59], v[166:169], v[174:177], v[56:59]
	v_mfma_f32_16x16x32_bf16 v[44:47], v[148:151], v[186:189], v[44:47]
	v_mfma_f32_16x16x32_bf16 v[40:43], v[166:169], v[186:189], v[40:43]
	v_mfma_f32_16x16x32_bf16 v[28:31], v[148:151], v[198:201], v[28:31]
	v_mfma_f32_16x16x32_bf16 v[24:27], v[166:169], v[198:201], v[24:27]
	v_mfma_f32_16x16x32_bf16 v[12:15], v[148:151], v[206:209], v[12:15]
	v_mfma_f32_16x16x32_bf16 v[8:11], v[166:169], v[206:209], v[8:11]
	v_mfma_f32_16x16x32_bf16 v[52:55], v[210:213], v[170:173], v[52:55]
	v_mfma_f32_16x16x32_bf16 v[48:51], v[218:221], v[170:173], v[48:51]
	v_mfma_f32_16x16x32_bf16 v[36:39], v[210:213], v[178:181], v[36:39]
	v_mfma_f32_16x16x32_bf16 v[32:35], v[218:221], v[178:181], v[32:35]
	v_mfma_f32_16x16x32_bf16 v[20:23], v[210:213], v[194:197], v[20:23]
	v_mfma_f32_16x16x32_bf16 v[16:19], v[218:221], v[194:197], v[16:19]
	v_mfma_f32_16x16x32_bf16 v[4:7], v[210:213], v[202:205], v[4:7]
	v_mfma_f32_16x16x32_bf16 v[0:3], v[218:221], v[202:205], v[0:3]
	v_mfma_f32_16x16x32_bf16 v[52:55], v[214:217], v[174:177], v[52:55]
	v_mfma_f32_16x16x32_bf16 v[48:51], v[222:225], v[174:177], v[48:51]
	v_mfma_f32_16x16x32_bf16 v[36:39], v[214:217], v[186:189], v[36:39]
	v_mfma_f32_16x16x32_bf16 v[32:35], v[222:225], v[186:189], v[32:35]
	v_mfma_f32_16x16x32_bf16 v[20:23], v[214:217], v[198:201], v[20:23]
	v_mfma_f32_16x16x32_bf16 v[16:19], v[222:225], v[198:201], v[16:19]
	v_mfma_f32_16x16x32_bf16 v[4:7], v[214:217], v[206:209], v[4:7]
	v_mfma_f32_16x16x32_bf16 v[0:3], v[222:225], v[206:209], v[0:3]
	s_setprio 0
	s_barrier
	s_cbranch_scc0 .LBB0_181
	s_sub_i32 s2, s6, 36
	v_lshl_add_u32 v146, s26, 8, v154
	s_cmp_gt_u32 s2, 15
	s_cselect_b64 s[28:29], -1, 0
	s_cmp_eq_u32 s6, 52
	v_ashrrev_i32_e32 v147, 31, v146
	v_mad_i64_i32 v[152:153], s[2:3], v146, s50, 0
	v_lshl_or_b32 v144, s6, 8, v156
	s_cselect_b64 s[26:27], -1, 0
	v_lshlrev_b64 v[150:151], 7, v[146:147]
	s_mov_b64 s[2:3], -1
	s_and_b64 vcc, exec, s[28:29]
	s_cbranch_vccz .LBB0_186
	v_lshl_add_u64 v[148:149], s[92:93], 0, v[152:153]
	v_ashrrev_i32_e32 v145, 31, v144
	v_cmp_gt_i32_e32 vcc, s52, v144
	v_lshl_add_u64 v[148:149], v[144:145], 1, v[148:149]
	s_and_b64 s[2:3], s[26:27], vcc
	v_cvt_pk_bf16_f32 v162, v124, v125
	v_cvt_pk_bf16_f32 v163, v126, v127
	v_cvt_pk_bf16_f32 v164, v120, v121
	v_cvt_pk_bf16_f32 v165, v122, v123
	global_store_dwordx4 v[148:149], v[162:165], off
	s_and_saveexec_b64 s[6:7], s[2:3]
	s_cbranch_execz .LBB0_185
	v_lshl_add_u64 v[148:149], s[14:15], 0, v[150:151]
	v_lshl_add_u64 v[148:149], v[144:145], 2, v[148:149]
	v_add_co_u32_e32 v162, vcc, 0xffff3000, v148
	s_nop 1
	v_addc_co_u32_e32 v163, vcc, -1, v149, vcc
	v_add_co_u32_e32 v148, vcc, 0xffff4000, v148
	global_store_dwordx4 v[162:163], v[124:127], off
	s_nop 0
	v_addc_co_u32_e32 v149, vcc, -1, v149, vcc
	global_store_dwordx4 v[148:149], v[120:123], off offset:-4080

.LBB0_903:
	s_add_u32 s24, s30, 0xfff00080
	s_addc_u32 s25, s31, -1
	s_add_i32 s29, 0, 0x10000
	v_add_u32_e32 v0, s29, v204
	ds_read_b128 v[132:135], v0
	ds_read_b128 v[136:139], v0 offset:1024
	ds_read_b128 v[140:143], v0 offset:2048
	ds_read_b128 v[144:147], v0 offset:3072
	s_cmp_eq_u32 s27, 28
	s_cselect_b32 s35, s1, s25
	s_cselect_b32 s34, s0, s24
	s_cselect_b32 s25, s39, s3
	s_cselect_b32 s24, s38, s2
	v_lshl_add_u64 v[2:3], s[30:31], 0, v[188:189]
	s_add_i32 m0, s46, 0xc000
	ds_read_b128 v[148:151], v206
	ds_read_b128 v[152:155], v206 offset:1024
	ds_read_b128 v[156:159], v206 offset:2048
	ds_read_b128 v[160:163], v206 offset:3072
	ds_read_b128 v[164:167], v206 offset:4096
	ds_read_b128 v[168:171], v206 offset:5120
	ds_read_b128 v[208:211], v206 offset:6144
	ds_read_b128 v[212:215], v206 offset:7168
	global_load_lds_dwordx4 v[2:3], off
	v_lshl_add_u64 v[2:3], s[30:31], 0, v[190:191]
	s_add_i32 m0, s46, 0xe000
	s_nop 0
	global_load_lds_dwordx4 v[2:3], off
	v_add_u32_e32 v0, 0x14000, v204
	ds_read_b128 v[216:219], v0
	ds_read_b128 v[220:223], v0 offset:1024
	ds_read_b128 v[224:227], v0 offset:2048
	ds_read_b128 v[228:231], v0 offset:3072
	s_waitcnt lgkmcnt(0)
	s_barrier
	s_setprio 1
	v_mfma_f32_16x16x32_bf16 v[2:5], v[132:135], v[148:151], v[4:7]
	v_mfma_f32_16x16x32_bf16 v[6:9], v[140:143], v[148:151], v[8:11]
	v_mfma_f32_16x16x32_bf16 v[12:15], v[132:135], v[156:159], v[12:15]
	v_mfma_f32_16x16x32_bf16 v[16:19], v[140:143], v[156:159], v[16:19]
	v_mfma_f32_16x16x32_bf16 v[20:23], v[132:135], v[164:167], v[20:23]
	v_mfma_f32_16x16x32_bf16 v[24:27], v[140:143], v[164:167], v[24:27]
	v_mfma_f32_16x16x32_bf16 v[28:31], v[132:135], v[208:211], v[28:31]
	v_mfma_f32_16x16x32_bf16 v[32:35], v[140:143], v[208:211], v[32:35]
	v_mfma_f32_16x16x32_bf16 v[2:5], v[136:139], v[152:155], v[2:5]
	v_mfma_f32_16x16x32_bf16 v[8:11], v[144:147], v[152:155], v[6:9]
	v_mfma_f32_16x16x32_bf16 v[12:15], v[136:139], v[160:163], v[12:15]
	v_mfma_f32_16x16x32_bf16 v[16:19], v[144:147], v[160:163], v[16:19]
	v_mfma_f32_16x16x32_bf16 v[20:23], v[136:139], v[168:171], v[20:23]
	v_mfma_f32_16x16x32_bf16 v[24:27], v[144:147], v[168:171], v[24:27]
	v_mfma_f32_16x16x32_bf16 v[28:31], v[136:139], v[212:215], v[28:31]
	v_mfma_f32_16x16x32_bf16 v[32:35], v[144:147], v[212:215], v[32:35]
	v_mfma_f32_16x16x32_bf16 v[36:39], v[216:219], v[148:151], v[36:39]
	v_mfma_f32_16x16x32_bf16 v[40:43], v[224:227], v[148:151], v[40:43]
	v_mfma_f32_16x16x32_bf16 v[44:47], v[216:219], v[156:159], v[44:47]
	v_mfma_f32_16x16x32_bf16 v[48:51], v[224:227], v[156:159], v[48:51]
	v_mfma_f32_16x16x32_bf16 v[52:55], v[216:219], v[164:167], v[52:55]
	v_mfma_f32_16x16x32_bf16 v[56:59], v[224:227], v[164:167], v[56:59]
	v_mfma_f32_16x16x32_bf16 v[60:63], v[216:219], v[208:211], v[60:63]
	v_mfma_f32_16x16x32_bf16 v[64:67], v[224:227], v[208:211], v[64:67]
	v_mfma_f32_16x16x32_bf16 v[36:39], v[220:223], v[152:155], v[36:39]
	v_mfma_f32_16x16x32_bf16 v[40:43], v[228:231], v[152:155], v[40:43]
	v_mfma_f32_16x16x32_bf16 v[44:47], v[220:223], v[160:163], v[44:47]
	v_mfma_f32_16x16x32_bf16 v[48:51], v[228:231], v[160:163], v[48:51]
	v_mfma_f32_16x16x32_bf16 v[52:55], v[220:223], v[168:171], v[52:55]
	v_mfma_f32_16x16x32_bf16 v[56:59], v[228:231], v[168:171], v[56:59]
	v_mfma_f32_16x16x32_bf16 v[60:63], v[220:223], v[212:215], v[60:63]
	v_mfma_f32_16x16x32_bf16 v[64:67], v[228:231], v[212:215], v[64:67]
	s_setprio 0
	s_barrier
	s_add_i32 s73, 0, 0x14000
	s_add_i32 s29, s29, s41
	v_lshl_add_u64 v[232:233], s[24:25], 0, v[184:185]
	s_mov_b32 m0, s29
	s_nop 0
	global_load_lds_dwordx4 v[232:233], off
	v_lshl_add_u64 v[234:235], s[24:25], 0, v[180:181]
	s_add_i32 m0, s29, 0x2000
	s_nop 0
	global_load_lds_dwordx4 v[234:235], off
	s_mov_b32 m0, s46
	v_lshl_add_u64 v[236:237], s[34:35], 0, v[186:187]
	ds_read_b128 v[148:151], v206 offset:16384
	ds_read_b128 v[152:155], v206 offset:17408
	ds_read_b128 v[156:159], v206 offset:18432
	ds_read_b128 v[160:163], v206 offset:19456
	ds_read_b128 v[164:167], v206 offset:20480
	ds_read_b128 v[168:171], v206 offset:21504
	ds_read_b128 v[208:211], v206 offset:22528
	ds_read_b128 v[212:215], v206 offset:23552
	global_load_lds_dwordx4 v[236:237], off
	v_lshl_add_u64 v[238:239], s[34:35], 0, v[182:183]
	s_mov_b32 m0, s47
	s_nop 0
	global_load_lds_dwordx4 v[238:239], off
	s_add_u32 s74, s24, 0x100000
	s_addc_u32 s75, s25, 0
	s_add_i32 s29, s73, s41
	v_lshl_add_u64 v[6:7], s[74:75], 0, v[184:185]
	s_mov_b32 m0, s29
	s_nop 0
	global_load_lds_dwordx4 v[6:7], off
	v_lshl_add_u64 v[6:7], s[74:75], 0, v[180:181]
	s_add_i32 m0, s29, 0x2000
	s_nop 0
	global_load_lds_dwordx4 v[6:7], off
	s_add_i32 s29, 0, 0x18000
	v_add_u32_e32 v0, s29, v204
	s_waitcnt vmcnt(6)
	s_waitcnt lgkmcnt(0)
	s_barrier
	s_setprio 1
	v_mfma_f32_16x16x32_bf16 v[68:71], v[132:135], v[148:151], v[68:71]
	v_mfma_f32_16x16x32_bf16 v[72:75], v[140:143], v[148:151], v[72:75]
	v_mfma_f32_16x16x32_bf16 v[76:79], v[132:135], v[156:159], v[76:79]
	v_mfma_f32_16x16x32_bf16 v[80:83], v[140:143], v[156:159], v[80:83]
	v_mfma_f32_16x16x32_bf16 v[84:87], v[132:135], v[164:167], v[84:87]
	v_mfma_f32_16x16x32_bf16 v[88:91], v[140:143], v[164:167], v[88:91]
	v_mfma_f32_16x16x32_bf16 v[92:95], v[132:135], v[208:211], v[92:95]
	v_mfma_f32_16x16x32_bf16 v[96:99], v[140:143], v[208:211], v[96:99]
	v_mfma_f32_16x16x32_bf16 v[68:71], v[136:139], v[152:155], v[68:71]
	v_mfma_f32_16x16x32_bf16 v[72:75], v[144:147], v[152:155], v[72:75]
	v_mfma_f32_16x16x32_bf16 v[76:79], v[136:139], v[160:163], v[76:79]
	v_mfma_f32_16x16x32_bf16 v[80:83], v[144:147], v[160:163], v[80:83]
	v_mfma_f32_16x16x32_bf16 v[84:87], v[136:139], v[168:171], v[84:87]
	v_mfma_f32_16x16x32_bf16 v[88:91], v[144:147], v[168:171], v[88:91]
	v_mfma_f32_16x16x32_bf16 v[92:95], v[136:139], v[212:215], v[92:95]
	v_mfma_f32_16x16x32_bf16 v[96:99], v[144:147], v[212:215], v[96:99]
	v_mfma_f32_16x16x32_bf16 v[100:103], v[216:219], v[148:151], v[100:103]
	v_mfma_f32_16x16x32_bf16 v[104:107], v[224:227], v[148:151], v[104:107]
	v_mfma_f32_16x16x32_bf16 v[108:111], v[216:219], v[156:159], v[108:111]
	v_mfma_f32_16x16x32_bf16 v[112:115], v[224:227], v[156:159], v[112:115]
	v_mfma_f32_16x16x32_bf16 v[116:119], v[216:219], v[164:167], v[116:119]
	v_mfma_f32_16x16x32_bf16 v[120:123], v[224:227], v[164:167], v[120:123]
	v_mfma_f32_16x16x32_bf16 v[124:127], v[216:219], v[208:211], v[124:127]
	v_mfma_f32_16x16x32_bf16 v[128:131], v[224:227], v[208:211], v[128:131]
	v_mfma_f32_16x16x32_bf16 v[100:103], v[220:223], v[152:155], v[100:103]
	v_mfma_f32_16x16x32_bf16 v[104:107], v[228:231], v[152:155], v[104:107]
	v_mfma_f32_16x16x32_bf16 v[108:111], v[220:223], v[160:163], v[108:111]
	v_mfma_f32_16x16x32_bf16 v[112:115], v[228:231], v[160:163], v[112:115]
	v_mfma_f32_16x16x32_bf16 v[116:119], v[220:223], v[168:171], v[116:119]
	v_mfma_f32_16x16x32_bf16 v[120:123], v[228:231], v[168:171], v[120:123]
	v_mfma_f32_16x16x32_bf16 v[124:127], v[220:223], v[212:215], v[124:127]
	v_mfma_f32_16x16x32_bf16 v[128:131], v[228:231], v[212:215], v[128:131]
	s_setprio 0
	s_barrier
	ds_read_b128 v[132:135], v0
	ds_read_b128 v[136:139], v0 offset:1024
	ds_read_b128 v[140:143], v0 offset:2048
	ds_read_b128 v[144:147], v0 offset:3072
	s_add_u32 s34, s34, 0x100000
	s_addc_u32 s35, s35, 0
	s_mov_b32 m0, s50
	v_lshl_add_u64 v[6:7], s[34:35], 0, v[186:187]
	ds_read_b128 v[148:151], v206 offset:32768
	ds_read_b128 v[152:155], v206 offset:33792
	ds_read_b128 v[156:159], v206 offset:34816
	ds_read_b128 v[160:163], v206 offset:35840
	ds_read_b128 v[164:167], v206 offset:36864
	ds_read_b128 v[168:171], v206 offset:37888
	ds_read_b128 v[208:211], v206 offset:38912
	ds_read_b128 v[212:215], v206 offset:39936
	global_load_lds_dwordx4 v[6:7], off
	v_lshl_add_u64 v[6:7], s[34:35], 0, v[182:183]
	s_mov_b32 m0, s51
	s_nop 0
	global_load_lds_dwordx4 v[6:7], off
	v_add_u32_e32 v0, 0x1c000, v204
	ds_read_b128 v[216:219], v0
	ds_read_b128 v[220:223], v0 offset:1024
	ds_read_b128 v[224:227], v0 offset:2048
	ds_read_b128 v[228:231], v0 offset:3072
	s_waitcnt lgkmcnt(0)
	s_barrier
	s_setprio 1
	v_mfma_f32_16x16x32_bf16 v[2:5], v[132:135], v[148:151], v[2:5]
	v_mfma_f32_16x16x32_bf16 v[8:11], v[140:143], v[148:151], v[8:11]
	v_mfma_f32_16x16x32_bf16 v[12:15], v[132:135], v[156:159], v[12:15]
	v_mfma_f32_16x16x32_bf16 v[16:19], v[140:143], v[156:159], v[16:19]
	v_mfma_f32_16x16x32_bf16 v[20:23], v[132:135], v[164:167], v[20:23]
	v_mfma_f32_16x16x32_bf16 v[24:27], v[140:143], v[164:167], v[24:27]
	v_mfma_f32_16x16x32_bf16 v[28:31], v[132:135], v[208:211], v[28:31]
	v_mfma_f32_16x16x32_bf16 v[32:35], v[140:143], v[208:211], v[32:35]
	v_mfma_f32_16x16x32_bf16 v[4:7], v[136:139], v[152:155], v[2:5]
	v_mfma_f32_16x16x32_bf16 v[8:11], v[144:147], v[152:155], v[8:11]
	v_mfma_f32_16x16x32_bf16 v[12:15], v[136:139], v[160:163], v[12:15]
	v_mfma_f32_16x16x32_bf16 v[16:19], v[144:147], v[160:163], v[16:19]
	v_mfma_f32_16x16x32_bf16 v[20:23], v[136:139], v[168:171], v[20:23]
	v_mfma_f32_16x16x32_bf16 v[24:27], v[144:147], v[168:171], v[24:27]
	v_mfma_f32_16x16x32_bf16 v[28:31], v[136:139], v[212:215], v[28:31]
	v_mfma_f32_16x16x32_bf16 v[32:35], v[144:147], v[212:215], v[32:35]
	v_mfma_f32_16x16x32_bf16 v[36:39], v[216:219], v[148:151], v[36:39]
	v_mfma_f32_16x16x32_bf16 v[40:43], v[224:227], v[148:151], v[40:43]
	v_mfma_f32_16x16x32_bf16 v[44:47], v[216:219], v[156:159], v[44:47]
	v_mfma_f32_16x16x32_bf16 v[48:51], v[224:227], v[156:159], v[48:51]
	v_mfma_f32_16x16x32_bf16 v[52:55], v[216:219], v[164:167], v[52:55]
	v_mfma_f32_16x16x32_bf16 v[56:59], v[224:227], v[164:167], v[56:59]
	v_mfma_f32_16x16x32_bf16 v[60:63], v[216:219], v[208:211], v[60:63]
	v_mfma_f32_16x16x32_bf16 v[64:67], v[224:227], v[208:211], v[64:67]
	v_mfma_f32_16x16x32_bf16 v[36:39], v[220:223], v[152:155], v[36:39]
	v_mfma_f32_16x16x32_bf16 v[40:43], v[228:231], v[152:155], v[40:43]
	v_mfma_f32_16x16x32_bf16 v[44:47], v[220:223], v[160:163], v[44:47]
	v_mfma_f32_16x16x32_bf16 v[48:51], v[228:231], v[160:163], v[48:51]
	v_mfma_f32_16x16x32_bf16 v[52:55], v[220:223], v[168:171], v[52:55]
	v_mfma_f32_16x16x32_bf16 v[56:59], v[228:231], v[168:171], v[56:59]
	v_mfma_f32_16x16x32_bf16 v[60:63], v[220:223], v[212:215], v[60:63]
	v_mfma_f32_16x16x32_bf16 v[64:67], v[228:231], v[212:215], v[64:67]
	s_setprio 0
	s_barrier
; __device__ __forceinline__ float bflo(unsigned w) { return __uint_as_float(w << 16); }
; __device__ __forceinline__ float bfhi(unsigned w) { return __uint_as_float(w & 0xffff0000u); }
; __device__ __forceinline__ unsigned pk2(float lo, float hi) { unsigned r; asm("v_cvt_pk_bf16_f32 %0, %1, %2" : "=v"(r) : "v"(lo), "v"(hi)); return r; }
;     __device__ __forceinline__ void operator()(const f32x4 (&acc)[2][2][4][2], const Unit& u, int wr, int wc, int fr, int fq) const {
;         const int row0 = u.pm * BM + wr * 64 + fr, col0 = u.pn * BM + wc * 32 + 8 * fq;
; #pragma unroll
;         for (int ai = 0; ai < 2; ++ai)
; #pragma unroll
;             for (int m = 0; m < 4; ++m) { const int row = row0 + ai * HALF + m * 16;
; #pragma unroll
;                 for (int bj = 0; bj < 2; ++bj) { const int col = col0 + bj * HALF;
;                     const u32x4 gp = *(const u32x4*)(proj + (size_t)row * NPROJ + C_GP + col);
;                     const f32x4 v0 = acc[ai][bj][m][0], v1 = acc[ai][bj][m][1];
;                     u32x4 w; w.x = pk2(v0[0] * bflo(gp.x), v0[1] * bfhi(gp.x)); w.y = pk2(v0[2] * bflo(gp.y), v0[3] * bfhi(gp.y));
;                     w.z = pk2(v1[0] * bflo(gp.z), v1[1] * bfhi(gp.z)); w.w = pk2(v1[2] * bflo(gp.w), v1[3] * bfhi(gp.w));
;                     *(u32x4*)(merged + (size_t)row * DM + col) = w; } }
	s_add_i32 s34, 0, 0x1c000
	s_add_i32 s29, s29, s41
	v_lshl_add_u64 v[2:3], v[232:233], 0, s[48:49]
	s_mov_b32 m0, s29
	s_nop 0
	global_load_lds_dwordx4 v[2:3], off
	v_lshl_add_u64 v[2:3], v[234:235], 0, s[48:49]
	s_add_i32 m0, s29, 0x2000
	s_nop 0
	global_load_lds_dwordx4 v[2:3], off
	s_mov_b32 m0, s56
	v_lshl_add_u64 v[2:3], v[236:237], 0, s[48:49]
	ds_read_b128 v[148:151], v206 offset:49152
	ds_read_b128 v[152:155], v206 offset:50176
	ds_read_b128 v[156:159], v206 offset:51200
	ds_read_b128 v[160:163], v206 offset:52224
	ds_read_b128 v[164:167], v206 offset:53248
	ds_read_b128 v[168:171], v206 offset:54272
	ds_read_b128 v[208:211], v206 offset:55296
	ds_read_b128 v[212:215], v206 offset:56320
	global_load_lds_dwordx4 v[2:3], off
	v_lshl_add_u64 v[2:3], v[238:239], 0, s[48:49]
	s_mov_b32 m0, s57
	s_nop 0
	global_load_lds_dwordx4 v[2:3], off
	s_add_u32 s24, s24, 0x100080
	s_addc_u32 s25, s25, 0
	s_add_i32 s29, s34, s41
	v_lshl_add_u64 v[2:3], s[24:25], 0, v[184:185]
	s_mov_b32 m0, s29
	s_nop 0
	global_load_lds_dwordx4 v[2:3], off
	v_lshl_add_u64 v[2:3], s[24:25], 0, v[180:181]
	s_add_i32 m0, s29, 0x2000
	s_nop 0
	global_load_lds_dwordx4 v[2:3], off
	s_add_i32 s27, s27, 2
	s_add_u32 s30, s30, 0x100
	s_addc_u32 s31, s31, 0
	s_add_u32 s2, s2, 0x100
	s_addc_u32 s3, s3, 0
	s_cmp_gt_u32 s27, 29
	s_waitcnt vmcnt(6)
	s_waitcnt lgkmcnt(0)
	s_barrier
	s_setprio 1
	v_mfma_f32_16x16x32_bf16 v[68:71], v[132:135], v[148:151], v[68:71]
	v_mfma_f32_16x16x32_bf16 v[72:75], v[140:143], v[148:151], v[72:75]
	v_mfma_f32_16x16x32_bf16 v[76:79], v[132:135], v[156:159], v[76:79]
	v_mfma_f32_16x16x32_bf16 v[80:83], v[140:143], v[156:159], v[80:83]
	v_mfma_f32_16x16x32_bf16 v[84:87], v[132:135], v[164:167], v[84:87]
	v_mfma_f32_16x16x32_bf16 v[88:91], v[140:143], v[164:167], v[88:91]
	v_mfma_f32_16x16x32_bf16 v[92:95], v[132:135], v[208:211], v[92:95]
	v_mfma_f32_16x16x32_bf16 v[96:99], v[140:143], v[208:211], v[96:99]
	v_mfma_f32_16x16x32_bf16 v[68:71], v[136:139], v[152:155], v[68:71]
	v_mfma_f32_16x16x32_bf16 v[72:75], v[144:147], v[152:155], v[72:75]
	v_mfma_f32_16x16x32_bf16 v[76:79], v[136:139], v[160:163], v[76:79]
	v_mfma_f32_16x16x32_bf16 v[80:83], v[144:147], v[160:163], v[80:83]
	v_mfma_f32_16x16x32_bf16 v[84:87], v[136:139], v[168:171], v[84:87]
	v_mfma_f32_16x16x32_bf16 v[88:91], v[144:147], v[168:171], v[88:91]
	v_mfma_f32_16x16x32_bf16 v[92:95], v[136:139], v[212:215], v[92:95]
	v_mfma_f32_16x16x32_bf16 v[96:99], v[144:147], v[212:215], v[96:99]
	v_mfma_f32_16x16x32_bf16 v[100:103], v[216:219], v[148:151], v[100:103]
	v_mfma_f32_16x16x32_bf16 v[104:107], v[224:227], v[148:151], v[104:107]
	v_mfma_f32_16x16x32_bf16 v[108:111], v[216:219], v[156:159], v[108:111]
	v_mfma_f32_16x16x32_bf16 v[112:115], v[224:227], v[156:159], v[112:115]
	v_mfma_f32_16x16x32_bf16 v[116:119], v[216:219], v[164:167], v[116:119]
	v_mfma_f32_16x16x32_bf16 v[120:123], v[224:227], v[164:167], v[120:123]
	v_mfma_f32_16x16x32_bf16 v[124:127], v[216:219], v[208:211], v[124:127]
	v_mfma_f32_16x16x32_bf16 v[128:131], v[224:227], v[208:211], v[128:131]
	v_mfma_f32_16x16x32_bf16 v[100:103], v[220:223], v[152:155], v[100:103]
	v_mfma_f32_16x16x32_bf16 v[104:107], v[228:231], v[152:155], v[104:107]
	v_mfma_f32_16x16x32_bf16 v[108:111], v[220:223], v[160:163], v[108:111]
	v_mfma_f32_16x16x32_bf16 v[112:115], v[228:231], v[160:163], v[112:115]
	v_mfma_f32_16x16x32_bf16 v[116:119], v[220:223], v[168:171], v[116:119]
	v_mfma_f32_16x16x32_bf16 v[120:123], v[228:231], v[168:171], v[120:123]
	v_mfma_f32_16x16x32_bf16 v[124:127], v[220:223], v[212:215], v[124:127]
	v_mfma_f32_16x16x32_bf16 v[128:131], v[228:231], v[212:215], v[128:131]
	s_setprio 0
	s_barrier
	s_cbranch_scc0 .LBB0_903
	s_cmp_lg_u32 s70, 0
	s_cselect_b64 s[30:31], -1, 0
	v_lshl_add_u32 v144, s72, 8, v203
	v_lshl_or_b32 v146, s71, 8, v205
	s_and_b64 vcc, exec, s[30:31]
	v_ashrrev_i32_e32 v147, 31, v146
	v_or_b32_e32 v142, 16, v144
	v_or_b32_e32 v140, 32, v144
	v_or_b32_e32 v138, 48, v144
	v_add_u32_e32 v136, 0x80, v144
	v_add_u32_e32 v134, 0x90, v144
	v_add_u32_e32 v132, 0xa0, v144
	v_add_u32_e32 v2, 0xb0, v144
	s_cbranch_vccz .LBB0_910
	v_mov_b64_e32 v[150:151], s[92:93]
	v_mad_i64_i32 v[148:149], s[2:3], v144, s91, v[150:151]
	v_lshl_add_u64 v[158:159], v[148:149], 0, s[76:77]
	v_lshlrev_b64 v[148:149], 1, v[146:147]
	v_lshl_add_u64 v[152:153], v[158:159], 0, v[148:149]
	v_mov_b32_e32 v170, v152
	v_mov_b32_e32 v171, v153
	s_mov_b32 s74, 0x0
	s_mov_b32 s75, 0
	v_lshl_add_u64 v[208:209], v[170:171], 0, s[74:75]
	global_load_dwordx4 v[208:211], v[208:209], off
	s_mov_b32 s74, 0x100
	s_mov_b32 s75, 0
	v_lshl_add_u64 v[212:213], v[170:171], 0, s[74:75]
	global_load_dwordx4 v[212:215], v[212:213], off
	s_mov_b32 s74, 0x6a000
	s_mov_b32 s75, 0
	v_lshl_add_u64 v[216:217], v[170:171], 0, s[74:75]
	global_load_dwordx4 v[216:219], v[216:217], off
	s_mov_b32 s74, 0x6a100
	s_mov_b32 s75, 0
	v_lshl_add_u64 v[220:221], v[170:171], 0, s[74:75]
	global_load_dwordx4 v[220:223], v[220:221], off
	s_mov_b32 s74, 0xd4000
	s_mov_b32 s75, 0
	v_lshl_add_u64 v[224:225], v[170:171], 0, s[74:75]
	global_load_dwordx4 v[224:227], v[224:225], off
	s_mov_b32 s74, 0xd4100
	s_mov_b32 s75, 0
	v_lshl_add_u64 v[228:229], v[170:171], 0, s[74:75]
	global_load_dwordx4 v[228:231], v[228:229], off
	s_mov_b32 s74, 0x13e000
	s_mov_b32 s75, 0
	v_lshl_add_u64 v[232:233], v[170:171], 0, s[74:75]
	global_load_dwordx4 v[232:235], v[232:233], off
	s_mov_b32 s74, 0x13e100
	s_mov_b32 s75, 0
	v_lshl_add_u64 v[236:237], v[170:171], 0, s[74:75]
	global_load_dwordx4 v[236:239], v[236:237], off
	s_mov_b32 s74, 0x350000
	s_mov_b32 s75, 0
	v_lshl_add_u64 v[166:167], v[170:171], 0, s[74:75]
	global_load_dwordx4 v[166:169], v[166:167], off
	s_mov_b32 s74, 0x350100
	s_mov_b32 s75, 0
	v_lshl_add_u64 v[246:247], v[170:171], 0, s[74:75]
	global_load_dwordx4 v[246:249], v[246:247], off
	s_mov_b32 s74, 0x3ba000
	s_mov_b32 s75, 0
	v_lshl_add_u64 v[250:251], v[170:171], 0, s[74:75]
	global_load_dwordx4 v[250:253], v[250:251], off
	v_ashrrev_i32_e32 v145, 31, v144
	v_readlane_b32 s4, v244, 47
	v_lshlrev_b64 v[156:157], 12, v[144:145]
	v_readlane_b32 s8, v244, 51
	v_readlane_b32 s9, v244, 52
	v_ashrrev_i32_e32 v143, 31, v142
	v_lshlrev_b64 v[162:163], 12, v[142:143]
	v_lshl_add_u64 v[156:157], s[8:9], 0, v[156:157]
	v_lshl_add_u64 v[160:161], v[156:157], 0, v[148:149]
	v_ashrrev_i32_e32 v141, 31, v140
	v_ashrrev_i32_e32 v139, 31, v138
	v_ashrrev_i32_e32 v137, 31, v136
	v_ashrrev_i32_e32 v135, 31, v134
	v_ashrrev_i32_e32 v133, 31, v132
	v_readlane_b32 s5, v244, 48
	v_readlane_b32 s6, v244, 49
	v_readlane_b32 s7, v244, 50
	v_readlane_b32 s10, v244, 53
	v_readlane_b32 s11, v244, 54
	s_waitcnt vmcnt(10)
; __device__ __forceinline__ float bflo(unsigned w) { return __uint_as_float(w << 16); }
; __device__ __forceinline__ float bfhi(unsigned w) { return __uint_as_float(w & 0xffff0000u); }
; __device__ __forceinline__ unsigned pk2(float lo, float hi) { unsigned r; asm("v_cvt_pk_bf16_f32 %0, %1, %2" : "=v"(r) : "v"(lo), "v"(hi)); return r; }
;     __device__ __forceinline__ void operator()(const f32x4 (&acc)[2][2][4][2], const Unit& u, int wr, int wc, int fr, int fq) const {
;         const int row0 = u.pm * BM + wr * 64 + fr, col0 = u.pn * BM + wc * 32 + 8 * fq;
; #pragma unroll
;         for (int ai = 0; ai < 2; ++ai)
; #pragma unroll
;             for (int m = 0; m < 4; ++m) { const int row = row0 + ai * HALF + m * 16;
; #pragma unroll
;                 for (int bj = 0; bj < 2; ++bj) { const int col = col0 + bj * HALF;
;                     const u32x4 gp = *(const u32x4*)(proj + (size_t)row * NPROJ + C_GP + col);
;                     const f32x4 v0 = acc[ai][bj][m][0], v1 = acc[ai][bj][m][1];
;                     u32x4 w; w.x = pk2(v0[0] * bflo(gp.x), v0[1] * bfhi(gp.x)); w.y = pk2(v0[2] * bflo(gp.y), v0[3] * bfhi(gp.y));
;                     w.z = pk2(v1[0] * bflo(gp.z), v1[1] * bfhi(gp.z)); w.w = pk2(v1[2] * bflo(gp.w), v1[3] * bfhi(gp.w));
;                     *(u32x4*)(merged + (size_t)row * DM + col) = w; } }
	v_mov_b32_e32 v152, v208
	v_mov_b32_e32 v153, v209
	v_mov_b32_e32 v154, v210
	v_mov_b32_e32 v155, v211
	s_mov_b32 s74, 0x3ba100
	s_mov_b32 s75, 0
	v_lshl_add_u64 v[208:209], v[170:171], 0, s[74:75]
	global_load_dwordx4 v[208:211], v[208:209], off
	v_lshlrev_b32_e32 v0, 16, v152
	v_and_b32_e32 v3, 0xffff0000, v152
	v_mul_f32_e32 v0, v4, v0
	v_mul_f32_e32 v3, v5, v3
	v_cvt_pk_bf16_f32 v152, v0, v3
	v_lshlrev_b32_e32 v0, 16, v153
	v_and_b32_e32 v3, 0xffff0000, v153
	v_mul_f32_e32 v0, v6, v0
	v_mul_f32_e32 v3, v7, v3
	v_cvt_pk_bf16_f32 v153, v0, v3
	v_lshlrev_b32_e32 v0, 16, v154
	v_and_b32_e32 v3, 0xffff0000, v154
	v_mul_f32_e32 v0, v8, v0
	v_mul_f32_e32 v3, v9, v3
	v_cvt_pk_bf16_f32 v154, v0, v3
	v_lshlrev_b32_e32 v0, 16, v155
	v_and_b32_e32 v3, 0xffff0000, v155
	v_mul_f32_e32 v0, v10, v0
	v_mul_f32_e32 v3, v11, v3
	v_cvt_pk_bf16_f32 v155, v0, v3
	global_store_dwordx4 v[160:161], v[152:155], off
	s_nop 1
	v_or_b32_e32 v152, 0x80, v146
	v_ashrrev_i32_e32 v153, 31, v152
	v_lshlrev_b64 v[152:153], 1, v[152:153]
	v_lshl_add_u64 v[154:155], v[158:159], 0, v[152:153]
	s_waitcnt vmcnt(11)
	v_mov_b32_e32 v154, v212
	v_mov_b32_e32 v155, v213
	v_mov_b32_e32 v156, v214
	v_mov_b32_e32 v157, v215
	s_mov_b32 s74, 0x424000
	s_mov_b32 s75, 0
	v_lshl_add_u64 v[212:213], v[170:171], 0, s[74:75]
	global_load_dwordx4 v[212:215], v[212:213], off
	v_lshlrev_b32_e32 v0, 16, v154
	v_and_b32_e32 v3, 0xffff0000, v154
	v_mul_f32_e32 v0, v36, v0
	v_mul_f32_e32 v3, v37, v3
	v_cvt_pk_bf16_f32 v154, v0, v3
	v_lshlrev_b32_e32 v0, 16, v155
	v_and_b32_e32 v3, 0xffff0000, v155
	v_mul_f32_e32 v0, v38, v0
	v_mul_f32_e32 v3, v39, v3
	v_cvt_pk_bf16_f32 v155, v0, v3
	v_lshlrev_b32_e32 v0, 16, v156
	v_and_b32_e32 v3, 0xffff0000, v156
	v_mul_f32_e32 v0, v40, v0
	v_mul_f32_e32 v3, v41, v3
	v_cvt_pk_bf16_f32 v156, v0, v3
	v_lshlrev_b32_e32 v0, 16, v157
	v_and_b32_e32 v3, 0xffff0000, v157
	v_mul_f32_e32 v0, v42, v0
	v_mul_f32_e32 v3, v43, v3
	v_cvt_pk_bf16_f32 v157, v0, v3
	global_store_dwordx4 v[160:161], v[154:157], off offset:256
	s_nop 1
	v_mad_i64_i32 v[154:155], s[2:3], v142, s91, v[150:151]
	v_lshl_add_u64 v[164:165], v[154:155], 0, s[76:77]
	v_lshl_add_u64 v[154:155], v[164:165], 0, v[148:149]
	s_waitcnt vmcnt(12)
	v_mov_b32_e32 v154, v216
	v_mov_b32_e32 v155, v217
	v_mov_b32_e32 v156, v218
	v_mov_b32_e32 v157, v219
	s_mov_b32 s74, 0x424100
	s_mov_b32 s75, 0
	v_lshl_add_u64 v[216:217], v[170:171], 0, s[74:75]
	global_load_dwordx4 v[216:219], v[216:217], off
	v_lshlrev_b32_e32 v0, 16, v154
	v_and_b32_e32 v3, 0xffff0000, v154
	v_mul_f32_e32 v0, v12, v0
	v_mul_f32_e32 v3, v13, v3
	v_cvt_pk_bf16_f32 v158, v0, v3
	v_lshlrev_b32_e32 v0, 16, v155
	v_and_b32_e32 v3, 0xffff0000, v155
	v_mul_f32_e32 v0, v14, v0
	v_mul_f32_e32 v3, v15, v3
	v_cvt_pk_bf16_f32 v159, v0, v3
	v_lshlrev_b32_e32 v0, 16, v156
	v_and_b32_e32 v3, 0xffff0000, v156
	v_mul_f32_e32 v0, v16, v0
	v_mul_f32_e32 v3, v17, v3
	v_lshl_add_u64 v[154:155], s[8:9], 0, v[162:163]
	v_cvt_pk_bf16_f32 v160, v0, v3
	v_lshlrev_b32_e32 v0, 16, v157
	v_and_b32_e32 v3, 0xffff0000, v157
	v_lshl_add_u64 v[154:155], v[154:155], 0, v[148:149]
	v_lshl_add_u64 v[156:157], v[164:165], 0, v[152:153]
	v_mul_f32_e32 v0, v18, v0
	v_mul_f32_e32 v3, v19, v3
	v_cvt_pk_bf16_f32 v161, v0, v3
	global_store_dwordx4 v[154:155], v[158:161], off
	v_lshlrev_b64 v[162:163], 12, v[140:141]
	s_waitcnt vmcnt(13)
	v_mov_b32_e32 v156, v220
	v_mov_b32_e32 v157, v221
	v_mov_b32_e32 v158, v222
	v_mov_b32_e32 v159, v223
	s_mov_b32 s74, 0x48e000
	s_mov_b32 s75, 0
	v_lshl_add_u64 v[220:221], v[170:171], 0, s[74:75]
	global_load_dwordx4 v[220:223], v[220:221], off
	v_lshlrev_b32_e32 v0, 16, v156
	v_and_b32_e32 v3, 0xffff0000, v156
	v_mul_f32_e32 v0, v44, v0
	v_mul_f32_e32 v3, v45, v3
	v_cvt_pk_bf16_f32 v156, v0, v3
	v_lshlrev_b32_e32 v0, 16, v157
	v_and_b32_e32 v3, 0xffff0000, v157
	v_mul_f32_e32 v0, v46, v0
	v_mul_f32_e32 v3, v47, v3
	v_cvt_pk_bf16_f32 v157, v0, v3
	v_lshlrev_b32_e32 v0, 16, v158
	v_and_b32_e32 v3, 0xffff0000, v158
	v_mul_f32_e32 v0, v48, v0
	v_mul_f32_e32 v3, v49, v3
	v_cvt_pk_bf16_f32 v158, v0, v3
	v_lshlrev_b32_e32 v0, 16, v159
	v_and_b32_e32 v3, 0xffff0000, v159
	v_mul_f32_e32 v0, v50, v0
	v_mul_f32_e32 v3, v51, v3
	v_cvt_pk_bf16_f32 v159, v0, v3
	global_store_dwordx4 v[154:155], v[156:159], off offset:256
	v_mad_i64_i32 v[154:155], s[2:3], v140, s91, v[150:151]
	v_lshl_add_u64 v[164:165], v[154:155], 0, s[76:77]
	v_lshl_add_u64 v[154:155], v[164:165], 0, v[148:149]
	s_waitcnt vmcnt(14)
	v_mov_b32_e32 v154, v224
	v_mov_b32_e32 v155, v225
	v_mov_b32_e32 v156, v226
	v_mov_b32_e32 v157, v227
	s_mov_b32 s74, 0x48e100
	s_mov_b32 s75, 0
	v_lshl_add_u64 v[224:225], v[170:171], 0, s[74:75]
	global_load_dwordx4 v[224:227], v[224:225], off
	v_lshlrev_b32_e32 v0, 16, v154
	v_and_b32_e32 v3, 0xffff0000, v154
	v_mul_f32_e32 v0, v20, v0
	v_mul_f32_e32 v3, v21, v3
	v_cvt_pk_bf16_f32 v158, v0, v3
	v_lshlrev_b32_e32 v0, 16, v155
	v_and_b32_e32 v3, 0xffff0000, v155
	v_mul_f32_e32 v0, v22, v0
	v_mul_f32_e32 v3, v23, v3
	v_cvt_pk_bf16_f32 v159, v0, v3
	v_lshlrev_b32_e32 v0, 16, v156
	v_and_b32_e32 v3, 0xffff0000, v156
	v_mul_f32_e32 v0, v24, v0
	v_mul_f32_e32 v3, v25, v3
	v_lshl_add_u64 v[154:155], s[8:9], 0, v[162:163]
	v_cvt_pk_bf16_f32 v160, v0, v3
	v_lshlrev_b32_e32 v0, 16, v157
	v_and_b32_e32 v3, 0xffff0000, v157
	v_lshl_add_u64 v[154:155], v[154:155], 0, v[148:149]
	v_lshl_add_u64 v[156:157], v[164:165], 0, v[152:153]
	v_mul_f32_e32 v0, v26, v0
	v_mul_f32_e32 v3, v27, v3
	v_cvt_pk_bf16_f32 v161, v0, v3
	global_store_dwordx4 v[154:155], v[158:161], off
	v_lshlrev_b64 v[162:163], 12, v[138:139]
	s_waitcnt vmcnt(15)
; __device__ __forceinline__ float bflo(unsigned w) { return __uint_as_float(w << 16); }
; __device__ __forceinline__ float bfhi(unsigned w) { return __uint_as_float(w & 0xffff0000u); }
; __device__ __forceinline__ unsigned pk2(float lo, float hi) { unsigned r; asm("v_cvt_pk_bf16_f32 %0, %1, %2" : "=v"(r) : "v"(lo), "v"(hi)); return r; }
;     __device__ __forceinline__ void operator()(const f32x4 (&acc)[2][2][4][2], const Unit& u, int wr, int wc, int fr, int fq) const {
;         const int row0 = u.pm * BM + wr * 64 + fr, col0 = u.pn * BM + wc * 32 + 8 * fq;
; #pragma unroll
;         for (int ai = 0; ai < 2; ++ai)
; #pragma unroll
;             for (int m = 0; m < 4; ++m) { const int row = row0 + ai * HALF + m * 16;
; #pragma unroll
;                 for (int bj = 0; bj < 2; ++bj) { const int col = col0 + bj * HALF;
;                     const u32x4 gp = *(const u32x4*)(proj + (size_t)row * NPROJ + C_GP + col);
;                     const f32x4 v0 = acc[ai][bj][m][0], v1 = acc[ai][bj][m][1];
;                     u32x4 w; w.x = pk2(v0[0] * bflo(gp.x), v0[1] * bfhi(gp.x)); w.y = pk2(v0[2] * bflo(gp.y), v0[3] * bfhi(gp.y));
;                     w.z = pk2(v1[0] * bflo(gp.z), v1[1] * bfhi(gp.z)); w.w = pk2(v1[2] * bflo(gp.w), v1[3] * bfhi(gp.w));
;                     *(u32x4*)(merged + (size_t)row * DM + col) = w; } }
	v_mov_b32_e32 v156, v228
	v_mov_b32_e32 v157, v229
	v_mov_b32_e32 v158, v230
	v_mov_b32_e32 v159, v231
	v_lshlrev_b32_e32 v0, 16, v156
	v_and_b32_e32 v3, 0xffff0000, v156
	v_mul_f32_e32 v0, v52, v0
	v_mul_f32_e32 v3, v53, v3
	v_cvt_pk_bf16_f32 v156, v0, v3
	v_lshlrev_b32_e32 v0, 16, v157
	v_and_b32_e32 v3, 0xffff0000, v157
	v_mul_f32_e32 v0, v54, v0
	v_mul_f32_e32 v3, v55, v3
	v_cvt_pk_bf16_f32 v157, v0, v3
	v_lshlrev_b32_e32 v0, 16, v158
	v_and_b32_e32 v3, 0xffff0000, v158
	v_mul_f32_e32 v0, v56, v0
	v_mul_f32_e32 v3, v57, v3
	v_cvt_pk_bf16_f32 v158, v0, v3
	v_lshlrev_b32_e32 v0, 16, v159
	v_and_b32_e32 v3, 0xffff0000, v159
	v_mul_f32_e32 v0, v58, v0
	v_mul_f32_e32 v3, v59, v3
	v_cvt_pk_bf16_f32 v159, v0, v3
	global_store_dwordx4 v[154:155], v[156:159], off offset:256
	v_mad_i64_i32 v[154:155], s[2:3], v138, s91, v[150:151]
	v_lshl_add_u64 v[164:165], v[154:155], 0, s[76:77]
	v_lshl_add_u64 v[154:155], v[164:165], 0, v[148:149]
	s_waitcnt vmcnt(15)
	v_mov_b32_e32 v154, v232
	v_mov_b32_e32 v155, v233
	v_mov_b32_e32 v156, v234
	v_mov_b32_e32 v157, v235
	v_lshlrev_b32_e32 v0, 16, v154
	v_and_b32_e32 v3, 0xffff0000, v154
	v_mul_f32_e32 v0, v28, v0
	v_mul_f32_e32 v3, v29, v3
	v_cvt_pk_bf16_f32 v158, v0, v3
	v_lshlrev_b32_e32 v0, 16, v155
	v_and_b32_e32 v3, 0xffff0000, v155
	v_mul_f32_e32 v0, v30, v0
	v_mul_f32_e32 v3, v31, v3
	v_cvt_pk_bf16_f32 v159, v0, v3
	v_lshlrev_b32_e32 v0, 16, v156
	v_and_b32_e32 v3, 0xffff0000, v156
	v_mul_f32_e32 v0, v32, v0
	v_mul_f32_e32 v3, v33, v3
	v_lshl_add_u64 v[154:155], s[8:9], 0, v[162:163]
	v_cvt_pk_bf16_f32 v160, v0, v3
	v_lshlrev_b32_e32 v0, 16, v157
	v_and_b32_e32 v3, 0xffff0000, v157
	v_lshl_add_u64 v[154:155], v[154:155], 0, v[148:149]
	v_lshl_add_u64 v[156:157], v[164:165], 0, v[152:153]
	v_mul_f32_e32 v0, v34, v0
	v_mul_f32_e32 v3, v35, v3
	v_cvt_pk_bf16_f32 v161, v0, v3
	global_store_dwordx4 v[154:155], v[158:161], off
	v_lshlrev_b64 v[162:163], 12, v[136:137]
	s_waitcnt vmcnt(15)
	v_mov_b32_e32 v156, v236
	v_mov_b32_e32 v157, v237
	v_mov_b32_e32 v158, v238
	v_mov_b32_e32 v159, v239
	v_lshlrev_b32_e32 v0, 16, v156
	v_and_b32_e32 v3, 0xffff0000, v156
	v_mul_f32_e32 v0, v60, v0
	v_mul_f32_e32 v3, v61, v3
	v_cvt_pk_bf16_f32 v156, v0, v3
	v_lshlrev_b32_e32 v0, 16, v157
	v_and_b32_e32 v3, 0xffff0000, v157
	v_mul_f32_e32 v0, v62, v0
	v_mul_f32_e32 v3, v63, v3
	v_cvt_pk_bf16_f32 v157, v0, v3
	v_lshlrev_b32_e32 v0, 16, v158
	v_and_b32_e32 v3, 0xffff0000, v158
	v_mul_f32_e32 v0, v64, v0
	v_mul_f32_e32 v3, v65, v3
	v_cvt_pk_bf16_f32 v158, v0, v3
	v_lshlrev_b32_e32 v0, 16, v159
	v_and_b32_e32 v3, 0xffff0000, v159
	v_mul_f32_e32 v0, v66, v0
	v_mul_f32_e32 v3, v67, v3
	v_cvt_pk_bf16_f32 v159, v0, v3
	global_store_dwordx4 v[154:155], v[156:159], off offset:256
	v_mad_i64_i32 v[154:155], s[2:3], v136, s91, v[150:151]
	v_lshl_add_u64 v[164:165], v[154:155], 0, s[76:77]
	v_lshl_add_u64 v[154:155], v[164:165], 0, v[148:149]
	s_waitcnt vmcnt(15)
	v_mov_b32_e32 v154, v166
	v_mov_b32_e32 v155, v167
	v_mov_b32_e32 v156, v168
	v_mov_b32_e32 v157, v169
	v_lshlrev_b32_e32 v0, 16, v154
	v_and_b32_e32 v3, 0xffff0000, v154
	v_mul_f32_e32 v0, v68, v0
	v_mul_f32_e32 v3, v69, v3
	v_cvt_pk_bf16_f32 v158, v0, v3
	v_lshlrev_b32_e32 v0, 16, v155
	v_and_b32_e32 v3, 0xffff0000, v155
	v_mul_f32_e32 v0, v70, v0
	v_mul_f32_e32 v3, v71, v3
	v_cvt_pk_bf16_f32 v159, v0, v3
	v_lshlrev_b32_e32 v0, 16, v156
	v_and_b32_e32 v3, 0xffff0000, v156
	v_mul_f32_e32 v0, v72, v0
	v_mul_f32_e32 v3, v73, v3
	v_lshl_add_u64 v[154:155], s[8:9], 0, v[162:163]
	v_cvt_pk_bf16_f32 v160, v0, v3
	v_lshlrev_b32_e32 v0, 16, v157
	v_and_b32_e32 v3, 0xffff0000, v157
	v_lshl_add_u64 v[154:155], v[154:155], 0, v[148:149]
	v_lshl_add_u64 v[156:157], v[164:165], 0, v[152:153]
	v_mul_f32_e32 v0, v74, v0
	v_mul_f32_e32 v3, v75, v3
	v_cvt_pk_bf16_f32 v161, v0, v3
	global_store_dwordx4 v[154:155], v[158:161], off
	v_lshlrev_b64 v[162:163], 12, v[134:135]
	s_waitcnt vmcnt(15)
	v_mov_b32_e32 v156, v246
	v_mov_b32_e32 v157, v247
	v_mov_b32_e32 v158, v248
	v_mov_b32_e32 v159, v249
	v_lshlrev_b32_e32 v0, 16, v156
	v_and_b32_e32 v3, 0xffff0000, v156
	v_mul_f32_e32 v0, v100, v0
	v_mul_f32_e32 v3, v101, v3
	v_cvt_pk_bf16_f32 v156, v0, v3
	v_lshlrev_b32_e32 v0, 16, v157
	v_and_b32_e32 v3, 0xffff0000, v157
	v_mul_f32_e32 v0, v102, v0
	v_mul_f32_e32 v3, v103, v3
	v_cvt_pk_bf16_f32 v157, v0, v3
	v_lshlrev_b32_e32 v0, 16, v158
	v_and_b32_e32 v3, 0xffff0000, v158
	v_mul_f32_e32 v0, v104, v0
	v_mul_f32_e32 v3, v105, v3
	v_cvt_pk_bf16_f32 v158, v0, v3
	v_lshlrev_b32_e32 v0, 16, v159
	v_and_b32_e32 v3, 0xffff0000, v159
	v_mul_f32_e32 v0, v106, v0
	v_mul_f32_e32 v3, v107, v3
	v_cvt_pk_bf16_f32 v159, v0, v3
	global_store_dwordx4 v[154:155], v[156:159], off offset:256
	v_mad_i64_i32 v[154:155], s[2:3], v134, s91, v[150:151]
	v_lshl_add_u64 v[164:165], v[154:155], 0, s[76:77]
	v_lshl_add_u64 v[154:155], v[164:165], 0, v[148:149]
	s_waitcnt vmcnt(15)
; __device__ __forceinline__ float bflo(unsigned w) { return __uint_as_float(w << 16); }
; __device__ __forceinline__ float bfhi(unsigned w) { return __uint_as_float(w & 0xffff0000u); }
; __device__ __forceinline__ unsigned pk2(float lo, float hi) { unsigned r; asm("v_cvt_pk_bf16_f32 %0, %1, %2" : "=v"(r) : "v"(lo), "v"(hi)); return r; }
;     __device__ __forceinline__ void operator()(const f32x4 (&acc)[2][2][4][2], const Unit& u, int wr, int wc, int fr, int fq) const {
;         const int row0 = u.pm * BM + wr * 64 + fr, col0 = u.pn * BM + wc * 32 + 8 * fq;
; #pragma unroll
;         for (int ai = 0; ai < 2; ++ai)
; #pragma unroll
;             for (int m = 0; m < 4; ++m) { const int row = row0 + ai * HALF + m * 16;
; #pragma unroll
;                 for (int bj = 0; bj < 2; ++bj) { const int col = col0 + bj * HALF;
;                     const u32x4 gp = *(const u32x4*)(proj + (size_t)row * NPROJ + C_GP + col);
;                     const f32x4 v0 = acc[ai][bj][m][0], v1 = acc[ai][bj][m][1];
;                     u32x4 w; w.x = pk2(v0[0] * bflo(gp.x), v0[1] * bfhi(gp.x)); w.y = pk2(v0[2] * bflo(gp.y), v0[3] * bfhi(gp.y));
;                     w.z = pk2(v1[0] * bflo(gp.z), v1[1] * bfhi(gp.z)); w.w = pk2(v1[2] * bflo(gp.w), v1[3] * bfhi(gp.w));
;                     *(u32x4*)(merged + (size_t)row * DM + col) = w; } }
	v_mov_b32_e32 v154, v250
	v_mov_b32_e32 v155, v251
	v_mov_b32_e32 v156, v252
	v_mov_b32_e32 v157, v253
	v_lshlrev_b32_e32 v0, 16, v154
	v_and_b32_e32 v3, 0xffff0000, v154
	v_mul_f32_e32 v0, v76, v0
	v_mul_f32_e32 v3, v77, v3
	v_cvt_pk_bf16_f32 v158, v0, v3
	v_lshlrev_b32_e32 v0, 16, v155
	v_and_b32_e32 v3, 0xffff0000, v155
	v_mul_f32_e32 v0, v78, v0
	v_mul_f32_e32 v3, v79, v3
	v_cvt_pk_bf16_f32 v159, v0, v3
	v_lshlrev_b32_e32 v0, 16, v156
	v_and_b32_e32 v3, 0xffff0000, v156
	v_mul_f32_e32 v0, v80, v0
	v_mul_f32_e32 v3, v81, v3
	v_lshl_add_u64 v[154:155], s[8:9], 0, v[162:163]
	v_cvt_pk_bf16_f32 v160, v0, v3
	v_lshlrev_b32_e32 v0, 16, v157
	v_and_b32_e32 v3, 0xffff0000, v157
	v_lshl_add_u64 v[154:155], v[154:155], 0, v[148:149]
	v_lshl_add_u64 v[156:157], v[164:165], 0, v[152:153]
	v_mul_f32_e32 v0, v82, v0
	v_mul_f32_e32 v3, v83, v3
	v_cvt_pk_bf16_f32 v161, v0, v3
	global_store_dwordx4 v[154:155], v[158:161], off
	v_lshlrev_b64 v[162:163], 12, v[132:133]
	s_waitcnt vmcnt(15)
	v_mov_b32_e32 v156, v208
	v_mov_b32_e32 v157, v209
	v_mov_b32_e32 v158, v210
	v_mov_b32_e32 v159, v211
	v_lshlrev_b32_e32 v0, 16, v156
	v_and_b32_e32 v3, 0xffff0000, v156
	v_mul_f32_e32 v0, v108, v0
	v_mul_f32_e32 v3, v109, v3
	v_cvt_pk_bf16_f32 v156, v0, v3
	v_lshlrev_b32_e32 v0, 16, v157
	v_and_b32_e32 v3, 0xffff0000, v157
	v_mul_f32_e32 v0, v110, v0
	v_mul_f32_e32 v3, v111, v3
	v_cvt_pk_bf16_f32 v157, v0, v3
	v_lshlrev_b32_e32 v0, 16, v158
	v_and_b32_e32 v3, 0xffff0000, v158
	v_mul_f32_e32 v0, v112, v0
	v_mul_f32_e32 v3, v113, v3
	v_cvt_pk_bf16_f32 v158, v0, v3
	v_lshlrev_b32_e32 v0, 16, v159
	v_and_b32_e32 v3, 0xffff0000, v159
	v_mul_f32_e32 v0, v114, v0
	v_mul_f32_e32 v3, v115, v3
	v_cvt_pk_bf16_f32 v159, v0, v3
	global_store_dwordx4 v[154:155], v[156:159], off offset:256
	v_mad_i64_i32 v[154:155], s[2:3], v132, s91, v[150:151]
	v_lshl_add_u64 v[164:165], v[154:155], 0, s[76:77]
	v_lshl_add_u64 v[154:155], v[164:165], 0, v[148:149]
	v_mad_i64_i32 v[150:151], s[2:3], v2, s91, v[150:151]
	v_lshl_add_u64 v[150:151], v[150:151], 0, s[76:77]
	s_waitcnt vmcnt(14)
	v_mov_b32_e32 v154, v212
	v_mov_b32_e32 v155, v213
	v_mov_b32_e32 v156, v214
	v_mov_b32_e32 v157, v215
	v_lshlrev_b32_e32 v0, 16, v154
	v_and_b32_e32 v3, 0xffff0000, v154
	v_mul_f32_e32 v0, v84, v0
	v_mul_f32_e32 v3, v85, v3
	v_cvt_pk_bf16_f32 v158, v0, v3
	v_lshlrev_b32_e32 v0, 16, v155
	v_and_b32_e32 v3, 0xffff0000, v155
	v_mul_f32_e32 v0, v86, v0
	v_mul_f32_e32 v3, v87, v3
	v_cvt_pk_bf16_f32 v159, v0, v3
	v_lshlrev_b32_e32 v0, 16, v156
	v_and_b32_e32 v3, 0xffff0000, v156
	v_mul_f32_e32 v0, v88, v0
	v_mul_f32_e32 v3, v89, v3
	v_lshl_add_u64 v[154:155], s[8:9], 0, v[162:163]
	v_cvt_pk_bf16_f32 v160, v0, v3
	v_lshlrev_b32_e32 v0, 16, v157
	v_and_b32_e32 v3, 0xffff0000, v157
	v_lshl_add_u64 v[154:155], v[154:155], 0, v[148:149]
	v_lshl_add_u64 v[156:157], v[164:165], 0, v[152:153]
	v_mul_f32_e32 v0, v90, v0
	v_mul_f32_e32 v3, v91, v3
	v_cvt_pk_bf16_f32 v161, v0, v3
	global_store_dwordx4 v[154:155], v[158:161], off
	s_waitcnt vmcnt(13)
	v_mov_b32_e32 v156, v216
	v_mov_b32_e32 v157, v217
	v_mov_b32_e32 v158, v218
	v_mov_b32_e32 v159, v219
	v_lshlrev_b32_e32 v0, 16, v156
	v_and_b32_e32 v3, 0xffff0000, v156
	v_mul_f32_e32 v0, v116, v0
	v_mul_f32_e32 v3, v117, v3
	v_cvt_pk_bf16_f32 v156, v0, v3
	v_lshlrev_b32_e32 v0, 16, v157
	v_and_b32_e32 v3, 0xffff0000, v157
	v_mul_f32_e32 v0, v118, v0
	v_mul_f32_e32 v3, v119, v3
	v_cvt_pk_bf16_f32 v157, v0, v3
	v_lshlrev_b32_e32 v0, 16, v158
	v_and_b32_e32 v3, 0xffff0000, v158
	v_mul_f32_e32 v0, v120, v0
	v_mul_f32_e32 v3, v121, v3
	v_cvt_pk_bf16_f32 v158, v0, v3
	v_lshlrev_b32_e32 v0, 16, v159
	v_and_b32_e32 v3, 0xffff0000, v159
	v_mul_f32_e32 v0, v122, v0
	v_mul_f32_e32 v3, v123, v3
	v_cvt_pk_bf16_f32 v159, v0, v3
	global_store_dwordx4 v[154:155], v[156:159], off offset:256
	v_lshl_add_u64 v[154:155], v[150:151], 0, v[148:149]
	v_lshl_add_u64 v[150:151], v[150:151], 0, v[152:153]
	v_ashrrev_i32_e32 v3, 31, v2
	v_lshlrev_b64 v[158:159], 12, v[2:3]
	v_lshl_add_u64 v[158:159], s[8:9], 0, v[158:159]
	v_lshl_add_u64 v[148:149], v[158:159], 0, v[148:149]
	s_waitcnt vmcnt(10)
	v_mov_b32_e32 v154, v220
	v_mov_b32_e32 v155, v221
	v_mov_b32_e32 v156, v222
	v_mov_b32_e32 v157, v223
	v_mov_b32_e32 v150, v224
	v_mov_b32_e32 v151, v225
	v_mov_b32_e32 v152, v226
	v_mov_b32_e32 v153, v227
	v_lshlrev_b32_e32 v0, 16, v154
	v_and_b32_e32 v3, 0xffff0000, v154
	v_mul_f32_e32 v0, v92, v0
	v_mul_f32_e32 v3, v93, v3
	v_cvt_pk_bf16_f32 v154, v0, v3
	v_lshlrev_b32_e32 v0, 16, v155
	v_and_b32_e32 v3, 0xffff0000, v155
	v_mul_f32_e32 v0, v94, v0
	v_mul_f32_e32 v3, v95, v3
	v_cvt_pk_bf16_f32 v155, v0, v3
	v_lshlrev_b32_e32 v0, 16, v156
	v_and_b32_e32 v3, 0xffff0000, v156
	v_mul_f32_e32 v0, v96, v0
	v_mul_f32_e32 v3, v97, v3
	v_cvt_pk_bf16_f32 v156, v0, v3
	v_lshlrev_b32_e32 v0, 16, v157
	v_and_b32_e32 v3, 0xffff0000, v157
	v_mul_f32_e32 v0, v98, v0
	v_mul_f32_e32 v3, v99, v3
	v_cvt_pk_bf16_f32 v157, v0, v3
	v_lshlrev_b32_e32 v0, 16, v150
	v_and_b32_e32 v3, 0xffff0000, v150
	v_mul_f32_e32 v0, v124, v0
	v_mul_f32_e32 v3, v125, v3
	v_cvt_pk_bf16_f32 v150, v0, v3
	v_lshlrev_b32_e32 v0, 16, v151
	v_and_b32_e32 v3, 0xffff0000, v151
	v_mul_f32_e32 v0, v126, v0
	v_mul_f32_e32 v3, v127, v3
	v_cvt_pk_bf16_f32 v151, v0, v3
	v_lshlrev_b32_e32 v0, 16, v152
	v_and_b32_e32 v3, 0xffff0000, v152
	v_mul_f32_e32 v0, v128, v0
	v_mul_f32_e32 v3, v129, v3
	v_cvt_pk_bf16_f32 v152, v0, v3
	v_lshlrev_b32_e32 v0, 16, v153
	v_and_b32_e32 v3, 0xffff0000, v153
	global_store_dwordx4 v[148:149], v[154:157], off
	v_mul_f32_e32 v0, v130, v0
	v_mul_f32_e32 v3, v131, v3
	v_cvt_pk_bf16_f32 v153, v0, v3
	global_store_dwordx4 v[148:149], v[150:153], off offset:256
	s_cbranch_execnz .LBB0_907
